# attention unit loop: next unit index prefetched during the current unit (global atomic into v255), sink-pointer kernarg parked in spill lanes instead of a per-unit L2-bypassing load
# baseline (speedup 1.0000x reference)
; #define LAS __attribute__((address_space(3)))
; __device__ __forceinline__ const float* PIN(int i) { return (const float*)KARG(i); }
; __device__ __forceinline__ unsigned char* PWS() { return (unsigned char*)KARG(24); }
; __device__ __forceinline__ int TID() { int t = threadIdx.x; asm volatile("" : "+v"(t)); return t; }
; __device__ __forceinline__ void attn_unit(LAS unsigned char* lds, bf16_t* proj, const float* biasG, const float* sink, int s, int qb, int kh, int hp, bf16_t* dummy = nullptr) {
;     ...
;     { const float sk = sink[h] * LOG2E; m2[0] = sk; m2[1] = sk; lsum[0] = (kg == 0) ? 1.f : 0.f; lsum[1] = lsum[0]; }
; __device__ __forceinline__ void phase_attn(LAS unsigned char* lds, bf16_t* proj, int layer, int nseq, unsigned* ctr) {
;     LAS int* slot = (LAS int*)(lds + LDS_BYTES - 16);
;     const int total = nseq * 256;
;     const float* biasG = (const float*)(PWS() + OFF_BIAS);
;     for (;;) {
;         __syncthreads();
;         if (TID() == 0) *slot = (int)atomicAdd(ctr, 1u);
;         __syncthreads();
;         const int idx = *slot;
;         if (idx >= total) break;
;         attn_unit(lds, proj, biasG, PIN(14) + layer * 8, idx >> 8, (idx >> 2) & 63, (idx >> 1) & 1, idx & 1);
.Lmy_prio_skip:
	global_load_dwordx2 v[252:253], v[148:149], off offset:112 sc0 sc1
	s_waitcnt vmcnt(0)
	v_readfirstlane_b32 s2, v253
	v_readfirstlane_b32 s3, v252
	s_nop 1
	v_writelane_b32 v254, s2, 45
	v_writelane_b32 v254, s3, 46
	v_cmp_eq_u32_e32 vcc, 0, v178
	s_and_saveexec_b64 s[2:3], vcc
	s_cbranch_execz .Lmy_deal_pf0
	v_mov_b64_e32 v[2:3], s[72:73]
	global_atomic_add v255, v[2:3], v180, off sc0
.Lmy_deal_pf0:
	s_or_b64 exec, exec, s[2:3]
	s_branch .LBB0_654

; __device__ __forceinline__ const float* PIN(int i) { return (const float*)KARG(i); }
; __device__ __forceinline__ int TID() { int t = threadIdx.x; asm volatile("" : "+v"(t)); return t; }
; __device__ __forceinline__ void attn_unit(LAS unsigned char* lds, bf16_t* proj, const float* biasG, const float* sink, int s, int qb, int kh, int hp, bf16_t* dummy = nullptr) {
;     ...
;     { const float sk = sink[h] * LOG2E; m2[0] = sk; m2[1] = sk; lsum[0] = (kg == 0) ? 1.f : 0.f; lsum[1] = lsum[0]; }
; __device__ __forceinline__ void phase_attn(LAS unsigned char* lds, bf16_t* proj, int layer, int nseq, unsigned* ctr) {
;     ...
;     for (;;) {
;         __syncthreads();
;         if (TID() == 0) *slot = (int)atomicAdd(ctr, 1u);
;         __syncthreads();
;         const int idx = *slot;
;         if (idx >= total) break;
;         attn_unit(lds, proj, biasG, PIN(14) + layer * 8, idx >> 8, (idx >> 2) & 63, (idx >> 1) & 1, idx & 1);
.LBB0_654:
	v_mov_b32_e32 v1, v178
	s_barrier
	s_nop 0
	v_cmp_eq_u32_e32 vcc, 0, v1
	s_and_saveexec_b64 s[2:3], vcc
	s_cbranch_execz .LBB0_656
	v_readlane_b32 s4, v254, 3
	s_nop 1
	v_mov_b32_e32 v2, s4
	s_waitcnt vmcnt(0) lgkmcnt(0)
	ds_write_b32 v2, v255
	v_mov_b64_e32 v[2:3], s[72:73]
	global_atomic_add v255, v[2:3], v180, off sc0
.LBB0_656:
	s_or_b64 exec, exec, s[2:3]
	v_readlane_b32 s2, v254, 3
	s_waitcnt lgkmcnt(0)
	s_barrier
	v_mov_b32_e32 v1, s2
	ds_read_b32 v1, v1
	s_movk_i32 s2, 0x9ff
	s_waitcnt lgkmcnt(0)
	v_cmp_lt_i32_e32 vcc, s2, v1
	v_readfirstlane_b32 s6, v1
	s_mov_b64 s[2:3], -1
	s_cbranch_vccnz .LBB0_653
	s_bfe_u32 s7, s6, 0x10001
	s_lshl_b32 s3, s6, 1
	s_lshl_b32 s2, s7, 2
	s_and_b32 s3, s3, 2
	v_mov_b32_e32 v1, v178
	s_or_b32 s10, s2, s3
	s_movk_i32 s2, 0x202
	s_mov_b32 s61, 0x11848
	s_mov_b32 s60, 0x11844
	v_readlane_b32 s8, v254, 45
	v_readlane_b32 s9, v254, 46
	v_cmp_gt_i32_e32 vcc, s2, v1
	s_and_saveexec_b64 s[2:3], vcc
	s_mov_b32 s31, 0x11800
	s_mov_b32 s40, 0x11804
	s_cbranch_execz .LBB0_660
	v_readlane_b32 s4, v254, 4
	v_mov_b32_e32 v3, v1
	s_nop 0
	v_lshl_add_u32 v2, v1, 2, s4
	s_mov_b64 s[4:5], 0

; __global__ void __launch_bounds__(512) mega(Params p, int ph_lo, int ph_hi) {
	.amdhsa_kernel _Z4mega6Paramsii
		.amdhsa_group_segment_fixed_size 0
		.amdhsa_private_segment_fixed_size 0
		.amdhsa_kernarg_size 464
		.amdhsa_user_sgpr_count 2
		.amdhsa_user_sgpr_dispatch_ptr 0
		.amdhsa_user_sgpr_queue_ptr 0
		.amdhsa_user_sgpr_kernarg_segment_ptr 1
		.amdhsa_user_sgpr_dispatch_id 0
		.amdhsa_user_sgpr_kernarg_preload_length 0
		.amdhsa_user_sgpr_kernarg_preload_offset 0
		.amdhsa_user_sgpr_private_segment_size 0
		.amdhsa_uses_dynamic_stack 0
		.amdhsa_enable_private_segment 0
		.amdhsa_system_sgpr_workgroup_id_x 1
		.amdhsa_system_sgpr_workgroup_id_y 0
		.amdhsa_system_sgpr_workgroup_id_z 0
		.amdhsa_system_sgpr_workgroup_info 0
		.amdhsa_system_vgpr_workitem_id 2
		.amdhsa_next_free_vgpr 256
		.amdhsa_next_free_sgpr 100
		.amdhsa_accum_offset 256
		.amdhsa_reserve_vcc 1
		.amdhsa_float_round_mode_32 0
		.amdhsa_float_round_mode_16_64 0
		.amdhsa_float_denorm_mode_32 3
		.amdhsa_float_denorm_mode_16_64 3
		.amdhsa_dx10_clamp 1
		.amdhsa_ieee_mode 1
		.amdhsa_fp16_overflow 0
		.amdhsa_tg_split 0
		.amdhsa_exception_fp_ieee_invalid_op 0
		.amdhsa_exception_fp_denorm_src 0
		.amdhsa_exception_fp_ieee_div_zero 0
		.amdhsa_exception_fp_ieee_overflow 0
		.amdhsa_exception_fp_ieee_underflow 0
		.amdhsa_exception_fp_ieee_inexact 0
		.amdhsa_exception_int_div_zero 0
	.end_amdhsa_kernel

; __global__ void __launch_bounds__(512) mega(Params p, int ph_lo, int ph_hi) {
amdhsa.kernels:
  - .agpr_count:     0
    .args:
      - .offset:         0
        .size:           200
        .value_kind:     by_value
      - .offset:         200
        .size:           4
        .value_kind:     by_value
      - .offset:         204
        .size:           4
        .value_kind:     by_value
      - .offset:         208
        .size:           4
        .value_kind:     hidden_block_count_x
      - .offset:         212
        .size:           4
        .value_kind:     hidden_block_count_y
      - .offset:         216
        .size:           4
        .value_kind:     hidden_block_count_z
      - .offset:         220
        .size:           2
        .value_kind:     hidden_group_size_x
      - .offset:         222
        .size:           2
        .value_kind:     hidden_group_size_y
      - .offset:         224
        .size:           2
        .value_kind:     hidden_group_size_z
      - .offset:         226
        .size:           2
        .value_kind:     hidden_remainder_x
      - .offset:         228
        .size:           2
        .value_kind:     hidden_remainder_y
      - .offset:         230
        .size:           2
        .value_kind:     hidden_remainder_z
      - .offset:         248
        .size:           8
        .value_kind:     hidden_global_offset_x
      - .offset:         256
        .size:           8
        .value_kind:     hidden_global_offset_y
      - .offset:         264
        .size:           8
        .value_kind:     hidden_global_offset_z
      - .offset:         272
        .size:           2
        .value_kind:     hidden_grid_dims
      - .offset:         296
        .size:           8
        .value_kind:     hidden_multigrid_sync_arg
      - .offset:         328
        .size:           4
        .value_kind:     hidden_dynamic_lds_size
    .group_segment_fixed_size: 0
    .kernarg_segment_align: 8
    .kernarg_segment_size: 464
    .language:       OpenCL C
    .language_version:
      - 2
      - 0
    .max_flat_workgroup_size: 512
    .name:           _Z4mega6Paramsii
    .private_segment_fixed_size: 0
    .sgpr_count:     106
    .sgpr_spill_count: 64
    .symbol:         _Z4mega6Paramsii.kd
    .uniform_work_group_size: 1
    .uses_dynamic_stack: false
    .vgpr_count:     256
    .vgpr_spill_count: 0
    .wavefront_size: 64
